# grid barrier: XCD leaders add to one chip-wide arrival counter (1 atomic instead of 16), all workgroups poll it
# baseline (speedup 1.0000x reference)
; DEV unsigned xb_ld(unsigned* p) { return __hip_atomic_load(p, __ATOMIC_RELAXED, __HIP_MEMORY_SCOPE_AGENT); }
; DEV unsigned xb_add(unsigned* p, unsigned v) { return __hip_atomic_fetch_add(p, v, __ATOMIC_RELAXED, __HIP_MEMORY_SCOPE_AGENT); }
; #define XB_SPIN(cond, bar) do { unsigned _sp = 0; while (cond) { __builtin_amdgcn_s_sleep(1); \
;     if ((++_sp & 255u) == 0u) { if (xb_ld(&(bar)[XB_TMO])) break; if (_sp > XB_SPIN_CAP) { atomicAdd(&(bar)[XB_TMO], 1u); break; } } } } while (0)
; DEV void xcd_barrier(const XcdBarrier& b) {
;   asm volatile("s_waitcnt vmcnt(0)" ::: "memory");
;   __syncthreads();
;   if (threadIdx.x == 0) {
;     unsigned* bar = b.bar;
;     __builtin_amdgcn_s_waitcnt(0);
;     unsigned nloc = b.st[0], nx = b.st[1];
;     if (nloc == 0u) { xcd_barrier_complete(bar, b.x, nloc, nx); b.st[0] = nloc; b.st[1] = nx; }
;     const unsigned old = xb_add(&bar[XB_XSUB(b.x)], 1u);
;     const unsigned gen = old / nloc;
;     if (old + 1u == (gen + 1u) * nloc) {
;       __builtin_amdgcn_fence(__ATOMIC_RELEASE, "agent");
;       asm volatile("s_waitcnt vmcnt(0)" ::: "memory");
;       const unsigned og = xb_add(&bar[XB_TOP], 1u);
;       const unsigned tg = og / nx;
;       if (og + 1u == (tg + 1u) * nx) xb_add(&bar[XB_TOPGEN], 1u);
;       else XB_SPIN(xb_ld(&bar[XB_TOPGEN]) == tg, bar);
;       __builtin_amdgcn_fence(__ATOMIC_ACQUIRE, "agent");
;       xb_add(&bar[XB_XGEN(b.x)], 1u);
;       asm volatile("s_waitcnt vmcnt(0)" ::: "memory");
;     } else {
;       XB_SPIN(xb_ld(&bar[XB_XGEN(b.x)]) == gen, bar);
;       __builtin_amdgcn_fence(__ATOMIC_ACQUIRE, "agent");
;       asm volatile("s_waitcnt vmcnt(0)" ::: "memory");
;     }
;   }
;   __syncthreads();
; }
Lxb1_poll:
	s_or_b64 exec, exec, s[14:15]
	v_mov_b32_e32 v4, 0
	s_mov_b32 s6, 0

; DEV unsigned xb_ld(unsigned* p) { return __hip_atomic_load(p, __ATOMIC_RELAXED, __HIP_MEMORY_SCOPE_AGENT); }
; DEV unsigned xb_add(unsigned* p, unsigned v) { return __hip_atomic_fetch_add(p, v, __ATOMIC_RELAXED, __HIP_MEMORY_SCOPE_AGENT); }
; #define XB_SPIN(cond, bar) do { unsigned _sp = 0; while (cond) { __builtin_amdgcn_s_sleep(1); \
;     if ((++_sp & 255u) == 0u) { if (xb_ld(&(bar)[XB_TMO])) break; if (_sp > XB_SPIN_CAP) { atomicAdd(&(bar)[XB_TMO], 1u); break; } } } } while (0)
; DEV void xcd_barrier(const XcdBarrier& b) {
;     ...
;     const unsigned old = xb_add(&bar[XB_XSUB(b.x)], 1u);
;     const unsigned gen = old / nloc;
;     if (old + 1u == (gen + 1u) * nloc) {
;       __builtin_amdgcn_fence(__ATOMIC_RELEASE, "agent");
;       asm volatile("s_waitcnt vmcnt(0)" ::: "memory");
;       const unsigned og = xb_add(&bar[XB_TOP], 1u);
;       const unsigned tg = og / nx;
;       if (og + 1u == (tg + 1u) * nx) xb_add(&bar[XB_TOPGEN], 1u);
;       else XB_SPIN(xb_ld(&bar[XB_TOPGEN]) == tg, bar);
;       __builtin_amdgcn_fence(__ATOMIC_ACQUIRE, "agent");
;       xb_add(&bar[XB_XGEN(b.x)], 1u);
;       asm volatile("s_waitcnt vmcnt(0)" ::: "memory");
;     } else {
;       XB_SPIN(xb_ld(&bar[XB_XGEN(b.x)]) == gen, bar);
;       __builtin_amdgcn_fence(__ATOMIC_ACQUIRE, "agent");
;       asm volatile("s_waitcnt vmcnt(0)" ::: "memory");
Lxb2_poll:
	s_or_b64 exec, exec, s[4:5]
	v_mov_b32_e32 v4, 0
	s_mov_b32 s6, 0

; DEV unsigned xb_ld(unsigned* p) { return __hip_atomic_load(p, __ATOMIC_RELAXED, __HIP_MEMORY_SCOPE_AGENT); }
; DEV unsigned xb_add(unsigned* p, unsigned v) { return __hip_atomic_fetch_add(p, v, __ATOMIC_RELAXED, __HIP_MEMORY_SCOPE_AGENT); }
; #define XB_SPIN(cond, bar) do { unsigned _sp = 0; while (cond) { __builtin_amdgcn_s_sleep(1); \
;     if ((++_sp & 255u) == 0u) { if (xb_ld(&(bar)[XB_TMO])) break; if (_sp > XB_SPIN_CAP) { atomicAdd(&(bar)[XB_TMO], 1u); break; } } } } while (0)
; DEV void xcd_barrier(const XcdBarrier& b) {
;     ...
;     const unsigned old = xb_add(&bar[XB_XSUB(b.x)], 1u);
;     const unsigned gen = old / nloc;
;     if (old + 1u == (gen + 1u) * nloc) {
;       __builtin_amdgcn_fence(__ATOMIC_RELEASE, "agent");
;       asm volatile("s_waitcnt vmcnt(0)" ::: "memory");
;       const unsigned og = xb_add(&bar[XB_TOP], 1u);
;       const unsigned tg = og / nx;
;       if (og + 1u == (tg + 1u) * nx) xb_add(&bar[XB_TOPGEN], 1u);
;       else XB_SPIN(xb_ld(&bar[XB_TOPGEN]) == tg, bar);
;       __builtin_amdgcn_fence(__ATOMIC_ACQUIRE, "agent");
;       xb_add(&bar[XB_XGEN(b.x)], 1u);
;       asm volatile("s_waitcnt vmcnt(0)" ::: "memory");
;     } else {
;       XB_SPIN(xb_ld(&bar[XB_XGEN(b.x)]) == gen, bar);
;       __builtin_amdgcn_fence(__ATOMIC_ACQUIRE, "agent");
;       asm volatile("s_waitcnt vmcnt(0)" ::: "memory");
Lxb3_poll:
	s_or_b64 exec, exec, s[4:5]
	v_mov_b32_e32 v4, 0
	s_mov_b32 s6, 0

; DEV unsigned xb_ld(unsigned* p) { return __hip_atomic_load(p, __ATOMIC_RELAXED, __HIP_MEMORY_SCOPE_AGENT); }
; DEV unsigned xb_add(unsigned* p, unsigned v) { return __hip_atomic_fetch_add(p, v, __ATOMIC_RELAXED, __HIP_MEMORY_SCOPE_AGENT); }
; #define XB_SPIN(cond, bar) do { unsigned _sp = 0; while (cond) { __builtin_amdgcn_s_sleep(1); \
;     if ((++_sp & 255u) == 0u) { if (xb_ld(&(bar)[XB_TMO])) break; if (_sp > XB_SPIN_CAP) { atomicAdd(&(bar)[XB_TMO], 1u); break; } } } } while (0)
; DEV void xcd_barrier(const XcdBarrier& b) {
;     ...
;     const unsigned old = xb_add(&bar[XB_XSUB(b.x)], 1u);
;     const unsigned gen = old / nloc;
;     if (old + 1u == (gen + 1u) * nloc) {
;       __builtin_amdgcn_fence(__ATOMIC_RELEASE, "agent");
;       asm volatile("s_waitcnt vmcnt(0)" ::: "memory");
;       const unsigned og = xb_add(&bar[XB_TOP], 1u);
;       const unsigned tg = og / nx;
;       if (og + 1u == (tg + 1u) * nx) xb_add(&bar[XB_TOPGEN], 1u);
;       else XB_SPIN(xb_ld(&bar[XB_TOPGEN]) == tg, bar);
;       __builtin_amdgcn_fence(__ATOMIC_ACQUIRE, "agent");
;       xb_add(&bar[XB_XGEN(b.x)], 1u);
;       asm volatile("s_waitcnt vmcnt(0)" ::: "memory");
;     } else {
;       XB_SPIN(xb_ld(&bar[XB_XGEN(b.x)]) == gen, bar);
;       __builtin_amdgcn_fence(__ATOMIC_ACQUIRE, "agent");
;       asm volatile("s_waitcnt vmcnt(0)" ::: "memory");
Lxb4_poll:
	s_or_b64 exec, exec, s[4:5]
	v_mov_b32_e32 v4, 0
	s_mov_b32 s6, 0

; DEV unsigned xb_ld(unsigned* p) { return __hip_atomic_load(p, __ATOMIC_RELAXED, __HIP_MEMORY_SCOPE_AGENT); }
; DEV unsigned xb_add(unsigned* p, unsigned v) { return __hip_atomic_fetch_add(p, v, __ATOMIC_RELAXED, __HIP_MEMORY_SCOPE_AGENT); }
; #define XB_SPIN(cond, bar) do { unsigned _sp = 0; while (cond) { __builtin_amdgcn_s_sleep(1); \
;     if ((++_sp & 255u) == 0u) { if (xb_ld(&(bar)[XB_TMO])) break; if (_sp > XB_SPIN_CAP) { atomicAdd(&(bar)[XB_TMO], 1u); break; } } } } while (0)
; DEV void xcd_barrier(const XcdBarrier& b) {
;     ...
;     const unsigned old = xb_add(&bar[XB_XSUB(b.x)], 1u);
;     const unsigned gen = old / nloc;
;     if (old + 1u == (gen + 1u) * nloc) {
;       __builtin_amdgcn_fence(__ATOMIC_RELEASE, "agent");
;       asm volatile("s_waitcnt vmcnt(0)" ::: "memory");
;       const unsigned og = xb_add(&bar[XB_TOP], 1u);
;       const unsigned tg = og / nx;
;       if (og + 1u == (tg + 1u) * nx) xb_add(&bar[XB_TOPGEN], 1u);
;       else XB_SPIN(xb_ld(&bar[XB_TOPGEN]) == tg, bar);
;       __builtin_amdgcn_fence(__ATOMIC_ACQUIRE, "agent");
;       xb_add(&bar[XB_XGEN(b.x)], 1u);
;       asm volatile("s_waitcnt vmcnt(0)" ::: "memory");
;     } else {
;       XB_SPIN(xb_ld(&bar[XB_XGEN(b.x)]) == gen, bar);
;       __builtin_amdgcn_fence(__ATOMIC_ACQUIRE, "agent");
;       asm volatile("s_waitcnt vmcnt(0)" ::: "memory");
Lxb5_poll:
	s_or_b64 exec, exec, s[4:5]
	v_mov_b32_e32 v4, 0
	s_mov_b32 s6, 0

; DEV unsigned xb_ld(unsigned* p) { return __hip_atomic_load(p, __ATOMIC_RELAXED, __HIP_MEMORY_SCOPE_AGENT); }
; DEV unsigned xb_add(unsigned* p, unsigned v) { return __hip_atomic_fetch_add(p, v, __ATOMIC_RELAXED, __HIP_MEMORY_SCOPE_AGENT); }
; #define XB_SPIN(cond, bar) do { unsigned _sp = 0; while (cond) { __builtin_amdgcn_s_sleep(1); \
;     if ((++_sp & 255u) == 0u) { if (xb_ld(&(bar)[XB_TMO])) break; if (_sp > XB_SPIN_CAP) { atomicAdd(&(bar)[XB_TMO], 1u); break; } } } } while (0)
; DEV void xcd_barrier(const XcdBarrier& b) {
;     ...
;     const unsigned old = xb_add(&bar[XB_XSUB(b.x)], 1u);
;     const unsigned gen = old / nloc;
;     if (old + 1u == (gen + 1u) * nloc) {
;       __builtin_amdgcn_fence(__ATOMIC_RELEASE, "agent");
;       asm volatile("s_waitcnt vmcnt(0)" ::: "memory");
;       const unsigned og = xb_add(&bar[XB_TOP], 1u);
;       const unsigned tg = og / nx;
;       if (og + 1u == (tg + 1u) * nx) xb_add(&bar[XB_TOPGEN], 1u);
;       else XB_SPIN(xb_ld(&bar[XB_TOPGEN]) == tg, bar);
;       __builtin_amdgcn_fence(__ATOMIC_ACQUIRE, "agent");
;       xb_add(&bar[XB_XGEN(b.x)], 1u);
;       asm volatile("s_waitcnt vmcnt(0)" ::: "memory");
;     } else {
;       XB_SPIN(xb_ld(&bar[XB_XGEN(b.x)]) == gen, bar);
;       __builtin_amdgcn_fence(__ATOMIC_ACQUIRE, "agent");
;       asm volatile("s_waitcnt vmcnt(0)" ::: "memory");
Lxb6_poll:
	s_or_b64 exec, exec, s[4:5]
	v_mov_b32_e32 v4, 0
	s_mov_b32 s6, 0

; DEV unsigned xb_ld(unsigned* p) { return __hip_atomic_load(p, __ATOMIC_RELAXED, __HIP_MEMORY_SCOPE_AGENT); }
; DEV unsigned xb_add(unsigned* p, unsigned v) { return __hip_atomic_fetch_add(p, v, __ATOMIC_RELAXED, __HIP_MEMORY_SCOPE_AGENT); }
; #define XB_SPIN(cond, bar) do { unsigned _sp = 0; while (cond) { __builtin_amdgcn_s_sleep(1); \
;     if ((++_sp & 255u) == 0u) { if (xb_ld(&(bar)[XB_TMO])) break; if (_sp > XB_SPIN_CAP) { atomicAdd(&(bar)[XB_TMO], 1u); break; } } } } while (0)
; DEV void xcd_barrier(const XcdBarrier& b) {
;     ...
;     const unsigned old = xb_add(&bar[XB_XSUB(b.x)], 1u);
;     const unsigned gen = old / nloc;
;     if (old + 1u == (gen + 1u) * nloc) {
;       __builtin_amdgcn_fence(__ATOMIC_RELEASE, "agent");
;       asm volatile("s_waitcnt vmcnt(0)" ::: "memory");
;       const unsigned og = xb_add(&bar[XB_TOP], 1u);
;       const unsigned tg = og / nx;
;       if (og + 1u == (tg + 1u) * nx) xb_add(&bar[XB_TOPGEN], 1u);
;       else XB_SPIN(xb_ld(&bar[XB_TOPGEN]) == tg, bar);
;       __builtin_amdgcn_fence(__ATOMIC_ACQUIRE, "agent");
;       xb_add(&bar[XB_XGEN(b.x)], 1u);
;       asm volatile("s_waitcnt vmcnt(0)" ::: "memory");
;     } else {
;       XB_SPIN(xb_ld(&bar[XB_XGEN(b.x)]) == gen, bar);
;       __builtin_amdgcn_fence(__ATOMIC_ACQUIRE, "agent");
;       asm volatile("s_waitcnt vmcnt(0)" ::: "memory");
Lxb7_poll:
	s_or_b64 exec, exec, s[4:5]
	v_mov_b32_e32 v4, 0
	s_mov_b32 s6, 0

; DEV unsigned xb_ld(unsigned* p) { return __hip_atomic_load(p, __ATOMIC_RELAXED, __HIP_MEMORY_SCOPE_AGENT); }
; DEV unsigned xb_add(unsigned* p, unsigned v) { return __hip_atomic_fetch_add(p, v, __ATOMIC_RELAXED, __HIP_MEMORY_SCOPE_AGENT); }
; #define XB_SPIN(cond, bar) do { unsigned _sp = 0; while (cond) { __builtin_amdgcn_s_sleep(1); \
;     if ((++_sp & 255u) == 0u) { if (xb_ld(&(bar)[XB_TMO])) break; if (_sp > XB_SPIN_CAP) { atomicAdd(&(bar)[XB_TMO], 1u); break; } } } } while (0)
; DEV void xcd_barrier(const XcdBarrier& b) {
;     ...
;     const unsigned old = xb_add(&bar[XB_XSUB(b.x)], 1u);
;     const unsigned gen = old / nloc;
;     if (old + 1u == (gen + 1u) * nloc) {
;       __builtin_amdgcn_fence(__ATOMIC_RELEASE, "agent");
;       asm volatile("s_waitcnt vmcnt(0)" ::: "memory");
;       const unsigned og = xb_add(&bar[XB_TOP], 1u);
;       const unsigned tg = og / nx;
;       if (og + 1u == (tg + 1u) * nx) xb_add(&bar[XB_TOPGEN], 1u);
;       else XB_SPIN(xb_ld(&bar[XB_TOPGEN]) == tg, bar);
;       __builtin_amdgcn_fence(__ATOMIC_ACQUIRE, "agent");
;       xb_add(&bar[XB_XGEN(b.x)], 1u);
;       asm volatile("s_waitcnt vmcnt(0)" ::: "memory");
;     } else {
;       XB_SPIN(xb_ld(&bar[XB_XGEN(b.x)]) == gen, bar);
;       __builtin_amdgcn_fence(__ATOMIC_ACQUIRE, "agent");
;       asm volatile("s_waitcnt vmcnt(0)" ::: "memory");
Lxb8_poll:
	s_or_b64 exec, exec, s[4:5]
	v_mov_b32_e32 v4, 0
	s_mov_b32 s6, 0

; DEV unsigned xb_ld(unsigned* p) { return __hip_atomic_load(p, __ATOMIC_RELAXED, __HIP_MEMORY_SCOPE_AGENT); }
; DEV unsigned xb_add(unsigned* p, unsigned v) { return __hip_atomic_fetch_add(p, v, __ATOMIC_RELAXED, __HIP_MEMORY_SCOPE_AGENT); }
; #define XB_SPIN(cond, bar) do { unsigned _sp = 0; while (cond) { __builtin_amdgcn_s_sleep(1); \
;     if ((++_sp & 255u) == 0u) { if (xb_ld(&(bar)[XB_TMO])) break; if (_sp > XB_SPIN_CAP) { atomicAdd(&(bar)[XB_TMO], 1u); break; } } } } while (0)
; DEV void xcd_barrier(const XcdBarrier& b) {
;     ...
;     const unsigned old = xb_add(&bar[XB_XSUB(b.x)], 1u);
;     const unsigned gen = old / nloc;
;     if (old + 1u == (gen + 1u) * nloc) {
;       __builtin_amdgcn_fence(__ATOMIC_RELEASE, "agent");
;       asm volatile("s_waitcnt vmcnt(0)" ::: "memory");
;       const unsigned og = xb_add(&bar[XB_TOP], 1u);
;       const unsigned tg = og / nx;
;       if (og + 1u == (tg + 1u) * nx) xb_add(&bar[XB_TOPGEN], 1u);
;       else XB_SPIN(xb_ld(&bar[XB_TOPGEN]) == tg, bar);
;       __builtin_amdgcn_fence(__ATOMIC_ACQUIRE, "agent");
;       xb_add(&bar[XB_XGEN(b.x)], 1u);
;       asm volatile("s_waitcnt vmcnt(0)" ::: "memory");
;     } else {
;       XB_SPIN(xb_ld(&bar[XB_XGEN(b.x)]) == gen, bar);
;       __builtin_amdgcn_fence(__ATOMIC_ACQUIRE, "agent");
;       asm volatile("s_waitcnt vmcnt(0)" ::: "memory");
Lxb9_poll:
	s_or_b64 exec, exec, s[14:15]
	v_mov_b32_e32 v4, 0
	s_mov_b32 s6, 0
